# FSsmY gelu epilogue: polynomial and +1 stages as packed f32 ops (v_pk_mul/v_pk_fma/v_pk_add with SGPR constants), 16 fewer VALU per 8 outputs
# speedup vs baseline: 1.0030x; 1.0030x over previous
; #define GAS __attribute__((address_space(1)))
; __device__ __forceinline__ float fexp2(float x) { return __builtin_amdgcn_exp2f(x); }
; __device__ __forceinline__ float frcp(float x) { return __builtin_amdgcn_rcpf(x); }
; __device__ __forceinline__ float gelu_tanh(float x) { const float u = 0.7978845608028654f * (x + 0.044715f * x * x * x); return x * sigmoidf_(2.f * u); }
; __device__ __forceinline__ u32x4 pack8(f32x4 a, f32x4 b) { u32x4 w; w.x = pk2(a[0], a[1]); w.y = pk2(a[2], a[3]); w.z = pk2(b[0], b[1]); w.w = pk2(b[2], b[3]); return w; }
; __device__ __forceinline__ float sigmoidf_(float x) { return frcp(1.f + fexp2(-x * LOG2E)); }
; __device__ __forceinline__ float siluf_(float x) { return x * sigmoidf_(x); }
;     __device__ __forceinline__ void operator()(const Unit& u, int row, int col, f32x4 v0, f32x4 v1) const {
;         const int g = row >> 11, rowg = row & 2047, j = col >> 4, p = col & 15;
; #pragma unroll
;         for (int i = 0; i < 4; ++i) { v0[i] = gelu_tanh(v0[i]); v1[i] = gelu_tanh(v1[i]); }
;         *(GAS u32x4*)(Y + ((size_t)(rowg * 16 + j) * 512 + g * 16 + p)) = pack8(v0, v1);
.LBB0_699:
	s_lshl_b32 s52, s72, 8
	s_add_i32 s52, s52, s85
	s_mov_b32 s98, 0xbdd2d3e8
	s_mov_b32 s100, 0xc0135761
	s_mov_b32 vcc_lo, 1.0
	v_or_b32_e32 v153, s52, v146
	v_lshlrev_b32_e32 v153, 4, v153
	v_and_b32_e32 v153, 0x7cf0, v153
	s_ashr_i32 s21, s52, 7
	s_and_b32 s50, s21, -16
	s_ashr_i32 s51, s50, 31
	s_lshl_b64 s[50:51], s[50:51], 1
	s_add_u32 s50, s50, s36
	s_addc_u32 s51, s51, s37
	v_add_u32_e32 v162, v153, v148
	v_add_u32_e32 v153, v153, v149
	v_lshl_add_u32 v162, v162, 10, v136
	v_lshl_add_u32 v153, v153, 10, v136
	v_pk_mul_f32 v[154:155], v[120:121], s[98:99] op_sel_hi:[1,0]
	v_pk_mul_f32 v[156:157], v[122:123], s[98:99] op_sel_hi:[1,0]
	v_pk_mul_f32 v[158:159], v[124:125], s[98:99] op_sel_hi:[1,0]
	v_pk_mul_f32 v[160:161], v[126:127], s[98:99] op_sel_hi:[1,0]
	v_pk_fma_f32 v[154:155], v[120:121], v[154:155], s[100:101] op_sel_hi:[1,1,0]
	v_pk_fma_f32 v[156:157], v[122:123], v[156:157], s[100:101] op_sel_hi:[1,1,0]
	v_pk_fma_f32 v[158:159], v[124:125], v[158:159], s[100:101] op_sel_hi:[1,1,0]
	v_pk_fma_f32 v[160:161], v[126:127], v[160:161], s[100:101] op_sel_hi:[1,1,0]
	v_pk_mul_f32 v[154:155], v[120:121], v[154:155]
	v_pk_mul_f32 v[156:157], v[122:123], v[156:157]
	v_pk_mul_f32 v[158:159], v[124:125], v[158:159]
	v_pk_mul_f32 v[160:161], v[126:127], v[160:161]
	v_exp_f32_e32 v154, v154
	v_exp_f32_e32 v155, v155
	v_exp_f32_e32 v156, v156
	v_exp_f32_e32 v157, v157
	v_exp_f32_e32 v158, v158
	v_exp_f32_e32 v159, v159
	v_exp_f32_e32 v160, v160
	v_exp_f32_e32 v161, v161
	v_pk_add_f32 v[154:155], v[154:155], vcc op_sel_hi:[1,0]
	v_pk_add_f32 v[156:157], v[156:157], vcc op_sel_hi:[1,0]
	v_pk_add_f32 v[158:159], v[158:159], vcc op_sel_hi:[1,0]
	v_pk_add_f32 v[160:161], v[160:161], vcc op_sel_hi:[1,0]
	v_rcp_f32_e32 v154, v154
	v_rcp_f32_e32 v155, v155
	v_rcp_f32_e32 v156, v156
	v_rcp_f32_e32 v157, v157
	v_rcp_f32_e32 v158, v158
	v_rcp_f32_e32 v159, v159
	v_rcp_f32_e32 v160, v160
	v_rcp_f32_e32 v161, v161
	v_pk_mul_f32 v[154:155], v[120:121], v[154:155]
	v_pk_mul_f32 v[156:157], v[122:123], v[156:157]
	v_pk_mul_f32 v[158:159], v[124:125], v[158:159]
	v_pk_mul_f32 v[160:161], v[126:127], v[160:161]
	v_cvt_pk_bf16_f32 v120, v158, v159
	v_cvt_pk_bf16_f32 v121, v160, v161
	v_cvt_pk_bf16_f32 v122, v154, v155
	v_cvt_pk_bf16_f32 v123, v156, v157
	global_store_dwordx4 v162, v[120:123], s[50:51]
	v_pk_mul_f32 v[154:155], v[112:113], s[98:99] op_sel_hi:[1,0]
	v_pk_mul_f32 v[156:157], v[114:115], s[98:99] op_sel_hi:[1,0]
	v_pk_mul_f32 v[158:159], v[116:117], s[98:99] op_sel_hi:[1,0]
	v_pk_mul_f32 v[160:161], v[118:119], s[98:99] op_sel_hi:[1,0]
	v_pk_fma_f32 v[154:155], v[112:113], v[154:155], s[100:101] op_sel_hi:[1,1,0]
	v_pk_fma_f32 v[156:157], v[114:115], v[156:157], s[100:101] op_sel_hi:[1,1,0]
	v_pk_fma_f32 v[158:159], v[116:117], v[158:159], s[100:101] op_sel_hi:[1,1,0]
	v_pk_fma_f32 v[160:161], v[118:119], v[160:161], s[100:101] op_sel_hi:[1,1,0]
	v_pk_mul_f32 v[154:155], v[112:113], v[154:155]
	v_pk_mul_f32 v[156:157], v[114:115], v[156:157]
	v_pk_mul_f32 v[158:159], v[116:117], v[158:159]
	v_pk_mul_f32 v[160:161], v[118:119], v[160:161]
	v_exp_f32_e32 v154, v154
	v_exp_f32_e32 v155, v155
	v_exp_f32_e32 v156, v156
	v_exp_f32_e32 v157, v157
	v_exp_f32_e32 v158, v158
	v_exp_f32_e32 v159, v159
	v_exp_f32_e32 v160, v160
	v_exp_f32_e32 v161, v161
	v_pk_add_f32 v[154:155], v[154:155], vcc op_sel_hi:[1,0]
	v_pk_add_f32 v[156:157], v[156:157], vcc op_sel_hi:[1,0]
	v_pk_add_f32 v[158:159], v[158:159], vcc op_sel_hi:[1,0]
	v_pk_add_f32 v[160:161], v[160:161], vcc op_sel_hi:[1,0]
	v_rcp_f32_e32 v154, v154
	v_rcp_f32_e32 v155, v155
	v_rcp_f32_e32 v156, v156
	v_rcp_f32_e32 v157, v157
	v_rcp_f32_e32 v158, v158
	v_rcp_f32_e32 v159, v159
	v_rcp_f32_e32 v160, v160
	v_rcp_f32_e32 v161, v161
	v_pk_mul_f32 v[154:155], v[112:113], v[154:155]
	v_pk_mul_f32 v[156:157], v[114:115], v[156:157]
	v_pk_mul_f32 v[158:159], v[116:117], v[158:159]
	v_pk_mul_f32 v[160:161], v[118:119], v[160:161]
	v_cvt_pk_bf16_f32 v112, v158, v159
	v_cvt_pk_bf16_f32 v113, v160, v161
	v_cvt_pk_bf16_f32 v114, v154, v155
	v_cvt_pk_bf16_f32 v115, v156, v157
	global_store_dwordx4 v153, v[112:115], s[50:51]
	s_add_u32 s50, s50, 0x40000
	s_addc_u32 s51, s51, 0
	v_pk_mul_f32 v[154:155], v[104:105], s[98:99] op_sel_hi:[1,0]
	v_pk_mul_f32 v[156:157], v[106:107], s[98:99] op_sel_hi:[1,0]
	v_pk_mul_f32 v[158:159], v[108:109], s[98:99] op_sel_hi:[1,0]
	v_pk_mul_f32 v[160:161], v[110:111], s[98:99] op_sel_hi:[1,0]
	v_pk_fma_f32 v[154:155], v[104:105], v[154:155], s[100:101] op_sel_hi:[1,1,0]
	v_pk_fma_f32 v[156:157], v[106:107], v[156:157], s[100:101] op_sel_hi:[1,1,0]
	v_pk_fma_f32 v[158:159], v[108:109], v[158:159], s[100:101] op_sel_hi:[1,1,0]
	v_pk_fma_f32 v[160:161], v[110:111], v[160:161], s[100:101] op_sel_hi:[1,1,0]
	v_pk_mul_f32 v[154:155], v[104:105], v[154:155]
	v_pk_mul_f32 v[156:157], v[106:107], v[156:157]
	v_pk_mul_f32 v[158:159], v[108:109], v[158:159]
	v_pk_mul_f32 v[160:161], v[110:111], v[160:161]
	v_exp_f32_e32 v154, v154
	v_exp_f32_e32 v155, v155
	v_exp_f32_e32 v156, v156
	v_exp_f32_e32 v157, v157
	v_exp_f32_e32 v158, v158
	v_exp_f32_e32 v159, v159
	v_exp_f32_e32 v160, v160
	v_exp_f32_e32 v161, v161
	v_pk_add_f32 v[154:155], v[154:155], vcc op_sel_hi:[1,0]
	v_pk_add_f32 v[156:157], v[156:157], vcc op_sel_hi:[1,0]
	v_pk_add_f32 v[158:159], v[158:159], vcc op_sel_hi:[1,0]
	v_pk_add_f32 v[160:161], v[160:161], vcc op_sel_hi:[1,0]
	v_rcp_f32_e32 v154, v154
	v_rcp_f32_e32 v155, v155
	v_rcp_f32_e32 v156, v156
	v_rcp_f32_e32 v157, v157
	v_rcp_f32_e32 v158, v158
	v_rcp_f32_e32 v159, v159
	v_rcp_f32_e32 v160, v160
	v_rcp_f32_e32 v161, v161
	v_pk_mul_f32 v[154:155], v[104:105], v[154:155]
; #define GAS __attribute__((address_space(1)))
; __device__ __forceinline__ float fexp2(float x) { return __builtin_amdgcn_exp2f(x); }
; __device__ __forceinline__ float frcp(float x) { return __builtin_amdgcn_rcpf(x); }
; __device__ __forceinline__ float gelu_tanh(float x) { const float u = 0.7978845608028654f * (x + 0.044715f * x * x * x); return x * sigmoidf_(2.f * u); }
; __device__ __forceinline__ u32x4 pack8(f32x4 a, f32x4 b) { u32x4 w; w.x = pk2(a[0], a[1]); w.y = pk2(a[2], a[3]); w.z = pk2(b[0], b[1]); w.w = pk2(b[2], b[3]); return w; }
; __device__ __forceinline__ float sigmoidf_(float x) { return frcp(1.f + fexp2(-x * LOG2E)); }
; __device__ __forceinline__ float siluf_(float x) { return x * sigmoidf_(x); }
;     __device__ __forceinline__ void operator()(const Unit& u, int row, int col, f32x4 v0, f32x4 v1) const {
;         const int g = row >> 11, rowg = row & 2047, j = col >> 4, p = col & 15;
; #pragma unroll
;         for (int i = 0; i < 4; ++i) { v0[i] = gelu_tanh(v0[i]); v1[i] = gelu_tanh(v1[i]); }
;         *(GAS u32x4*)(Y + ((size_t)(rowg * 16 + j) * 512 + g * 16 + p)) = pack8(v0, v1);
	v_pk_mul_f32 v[156:157], v[106:107], v[156:157]
	v_pk_mul_f32 v[158:159], v[108:109], v[158:159]
	v_pk_mul_f32 v[160:161], v[110:111], v[160:161]
	v_cvt_pk_bf16_f32 v104, v158, v159
	v_cvt_pk_bf16_f32 v105, v160, v161
	v_cvt_pk_bf16_f32 v106, v154, v155
	v_cvt_pk_bf16_f32 v107, v156, v157
	global_store_dwordx4 v162, v[104:107], s[50:51]
	v_pk_mul_f32 v[154:155], v[96:97], s[98:99] op_sel_hi:[1,0]
	v_pk_mul_f32 v[156:157], v[98:99], s[98:99] op_sel_hi:[1,0]
	v_pk_mul_f32 v[158:159], v[100:101], s[98:99] op_sel_hi:[1,0]
	v_pk_mul_f32 v[160:161], v[102:103], s[98:99] op_sel_hi:[1,0]
	v_pk_fma_f32 v[154:155], v[96:97], v[154:155], s[100:101] op_sel_hi:[1,1,0]
	v_pk_fma_f32 v[156:157], v[98:99], v[156:157], s[100:101] op_sel_hi:[1,1,0]
	v_pk_fma_f32 v[158:159], v[100:101], v[158:159], s[100:101] op_sel_hi:[1,1,0]
	v_pk_fma_f32 v[160:161], v[102:103], v[160:161], s[100:101] op_sel_hi:[1,1,0]
	v_pk_mul_f32 v[154:155], v[96:97], v[154:155]
	v_pk_mul_f32 v[156:157], v[98:99], v[156:157]
	v_pk_mul_f32 v[158:159], v[100:101], v[158:159]
	v_pk_mul_f32 v[160:161], v[102:103], v[160:161]
	v_exp_f32_e32 v154, v154
	v_exp_f32_e32 v155, v155
	v_exp_f32_e32 v156, v156
	v_exp_f32_e32 v157, v157
	v_exp_f32_e32 v158, v158
	v_exp_f32_e32 v159, v159
	v_exp_f32_e32 v160, v160
	v_exp_f32_e32 v161, v161
	v_pk_add_f32 v[154:155], v[154:155], vcc op_sel_hi:[1,0]
	v_pk_add_f32 v[156:157], v[156:157], vcc op_sel_hi:[1,0]
	v_pk_add_f32 v[158:159], v[158:159], vcc op_sel_hi:[1,0]
	v_pk_add_f32 v[160:161], v[160:161], vcc op_sel_hi:[1,0]
	v_rcp_f32_e32 v154, v154
	v_rcp_f32_e32 v155, v155
	v_rcp_f32_e32 v156, v156
	v_rcp_f32_e32 v157, v157
	v_rcp_f32_e32 v158, v158
	v_rcp_f32_e32 v159, v159
	v_rcp_f32_e32 v160, v160
	v_rcp_f32_e32 v161, v161
	v_pk_mul_f32 v[154:155], v[96:97], v[154:155]
	v_pk_mul_f32 v[156:157], v[98:99], v[156:157]
	v_pk_mul_f32 v[158:159], v[100:101], v[158:159]
	v_pk_mul_f32 v[160:161], v[102:103], v[160:161]
	v_cvt_pk_bf16_f32 v96, v158, v159
	v_cvt_pk_bf16_f32 v97, v160, v161
	v_cvt_pk_bf16_f32 v98, v154, v155
	v_cvt_pk_bf16_f32 v99, v156, v157
	global_store_dwordx4 v153, v[96:99], s[50:51]
	s_add_u32 s50, s50, 0x40000
	s_addc_u32 s51, s51, 0
	v_pk_mul_f32 v[154:155], v[88:89], s[98:99] op_sel_hi:[1,0]
	v_pk_mul_f32 v[156:157], v[90:91], s[98:99] op_sel_hi:[1,0]
	v_pk_mul_f32 v[158:159], v[92:93], s[98:99] op_sel_hi:[1,0]
	v_pk_mul_f32 v[160:161], v[94:95], s[98:99] op_sel_hi:[1,0]
	v_pk_fma_f32 v[154:155], v[88:89], v[154:155], s[100:101] op_sel_hi:[1,1,0]
	v_pk_fma_f32 v[156:157], v[90:91], v[156:157], s[100:101] op_sel_hi:[1,1,0]
	v_pk_fma_f32 v[158:159], v[92:93], v[158:159], s[100:101] op_sel_hi:[1,1,0]
	v_pk_fma_f32 v[160:161], v[94:95], v[160:161], s[100:101] op_sel_hi:[1,1,0]
	v_pk_mul_f32 v[154:155], v[88:89], v[154:155]
	v_pk_mul_f32 v[156:157], v[90:91], v[156:157]
	v_pk_mul_f32 v[158:159], v[92:93], v[158:159]
	v_pk_mul_f32 v[160:161], v[94:95], v[160:161]
	v_exp_f32_e32 v154, v154
	v_exp_f32_e32 v155, v155
	v_exp_f32_e32 v156, v156
	v_exp_f32_e32 v157, v157
	v_exp_f32_e32 v158, v158
	v_exp_f32_e32 v159, v159
	v_exp_f32_e32 v160, v160
	v_exp_f32_e32 v161, v161
	v_pk_add_f32 v[154:155], v[154:155], vcc op_sel_hi:[1,0]
	v_pk_add_f32 v[156:157], v[156:157], vcc op_sel_hi:[1,0]
	v_pk_add_f32 v[158:159], v[158:159], vcc op_sel_hi:[1,0]
	v_pk_add_f32 v[160:161], v[160:161], vcc op_sel_hi:[1,0]
	v_rcp_f32_e32 v154, v154
	v_rcp_f32_e32 v155, v155
	v_rcp_f32_e32 v156, v156
	v_rcp_f32_e32 v157, v157
	v_rcp_f32_e32 v158, v158
	v_rcp_f32_e32 v159, v159
	v_rcp_f32_e32 v160, v160
	v_rcp_f32_e32 v161, v161
	v_pk_mul_f32 v[154:155], v[88:89], v[154:155]
	v_pk_mul_f32 v[156:157], v[90:91], v[156:157]
	v_pk_mul_f32 v[158:159], v[92:93], v[158:159]
	v_pk_mul_f32 v[160:161], v[94:95], v[160:161]
	v_cvt_pk_bf16_f32 v88, v158, v159
	v_cvt_pk_bf16_f32 v89, v160, v161
	v_cvt_pk_bf16_f32 v90, v154, v155
	v_cvt_pk_bf16_f32 v91, v156, v157
	global_store_dwordx4 v162, v[88:91], s[50:51]
	v_pk_mul_f32 v[154:155], v[80:81], s[98:99] op_sel_hi:[1,0]
	v_pk_mul_f32 v[156:157], v[82:83], s[98:99] op_sel_hi:[1,0]
	v_pk_mul_f32 v[158:159], v[84:85], s[98:99] op_sel_hi:[1,0]
	v_pk_mul_f32 v[160:161], v[86:87], s[98:99] op_sel_hi:[1,0]
	v_pk_fma_f32 v[154:155], v[80:81], v[154:155], s[100:101] op_sel_hi:[1,1,0]
	v_pk_fma_f32 v[156:157], v[82:83], v[156:157], s[100:101] op_sel_hi:[1,1,0]
	v_pk_fma_f32 v[158:159], v[84:85], v[158:159], s[100:101] op_sel_hi:[1,1,0]
	v_pk_fma_f32 v[160:161], v[86:87], v[160:161], s[100:101] op_sel_hi:[1,1,0]
	v_pk_mul_f32 v[154:155], v[80:81], v[154:155]
	v_pk_mul_f32 v[156:157], v[82:83], v[156:157]
	v_pk_mul_f32 v[158:159], v[84:85], v[158:159]
	v_pk_mul_f32 v[160:161], v[86:87], v[160:161]
	v_exp_f32_e32 v154, v154
	v_exp_f32_e32 v155, v155
	v_exp_f32_e32 v156, v156
	v_exp_f32_e32 v157, v157
	v_exp_f32_e32 v158, v158
	v_exp_f32_e32 v159, v159
	v_exp_f32_e32 v160, v160
	v_exp_f32_e32 v161, v161
	v_pk_add_f32 v[154:155], v[154:155], vcc op_sel_hi:[1,0]
	v_pk_add_f32 v[156:157], v[156:157], vcc op_sel_hi:[1,0]
	v_pk_add_f32 v[158:159], v[158:159], vcc op_sel_hi:[1,0]
	v_pk_add_f32 v[160:161], v[160:161], vcc op_sel_hi:[1,0]
	v_rcp_f32_e32 v154, v154
	v_rcp_f32_e32 v155, v155
	v_rcp_f32_e32 v156, v156
	v_rcp_f32_e32 v157, v157
	v_rcp_f32_e32 v158, v158
	v_rcp_f32_e32 v159, v159
	v_rcp_f32_e32 v160, v160
	v_rcp_f32_e32 v161, v161
	v_pk_mul_f32 v[154:155], v[80:81], v[154:155]
	v_pk_mul_f32 v[156:157], v[82:83], v[156:157]
	v_pk_mul_f32 v[158:159], v[84:85], v[158:159]
	v_pk_mul_f32 v[160:161], v[86:87], v[160:161]
	v_cvt_pk_bf16_f32 v80, v158, v159
	v_cvt_pk_bf16_f32 v81, v160, v161
	v_cvt_pk_bf16_f32 v82, v154, v155
	v_cvt_pk_bf16_f32 v83, v156, v157
; #define GAS __attribute__((address_space(1)))
; __device__ __forceinline__ float gelu_tanh(float x) { const float u = 0.7978845608028654f * (x + 0.044715f * x * x * x); return x * sigmoidf_(2.f * u); }
; __device__ __forceinline__ u32x4 pack8(f32x4 a, f32x4 b) { u32x4 w; w.x = pk2(a[0], a[1]); w.y = pk2(a[2], a[3]); w.z = pk2(b[0], b[1]); w.w = pk2(b[2], b[3]); return w; }
;     __device__ __forceinline__ void operator()(const Unit& u, int row, int col, f32x4 v0, f32x4 v1) const {
;         const int g = row >> 11, rowg = row & 2047, j = col >> 4, p = col & 15;
; #pragma unroll
;         for (int i = 0; i < 4; ++i) { v0[i] = gelu_tanh(v0[i]); v1[i] = gelu_tanh(v1[i]); }
;         *(GAS u32x4*)(Y + ((size_t)(rowg * 16 + j) * 512 + g * 16 + p)) = pack8(v0, v1);
;     __device__ __forceinline__ void operator()(const f32x4 (&acc)[2][2][4][2], const Unit& u, int wr, int wc, int fr, int fq) const {
;     ...
;                 const int row = u.pm * 256 + ai * 128 + wr * 64 + m * 16 + fr;
	global_store_dwordx4 v153, v[80:83], s[50:51]
	s_add_u32 s50, s50, 0x40000
	s_addc_u32 s51, s51, 0
	v_pk_mul_f32 v[154:155], v[72:73], s[98:99] op_sel_hi:[1,0]
	v_pk_mul_f32 v[156:157], v[74:75], s[98:99] op_sel_hi:[1,0]
	v_pk_mul_f32 v[158:159], v[76:77], s[98:99] op_sel_hi:[1,0]
	v_pk_mul_f32 v[160:161], v[78:79], s[98:99] op_sel_hi:[1,0]
	v_pk_fma_f32 v[154:155], v[72:73], v[154:155], s[100:101] op_sel_hi:[1,1,0]
	v_pk_fma_f32 v[156:157], v[74:75], v[156:157], s[100:101] op_sel_hi:[1,1,0]
	v_pk_fma_f32 v[158:159], v[76:77], v[158:159], s[100:101] op_sel_hi:[1,1,0]
	v_pk_fma_f32 v[160:161], v[78:79], v[160:161], s[100:101] op_sel_hi:[1,1,0]
	v_pk_mul_f32 v[154:155], v[72:73], v[154:155]
	v_pk_mul_f32 v[156:157], v[74:75], v[156:157]
	v_pk_mul_f32 v[158:159], v[76:77], v[158:159]
	v_pk_mul_f32 v[160:161], v[78:79], v[160:161]
	v_exp_f32_e32 v154, v154
	v_exp_f32_e32 v155, v155
	v_exp_f32_e32 v156, v156
	v_exp_f32_e32 v157, v157
	v_exp_f32_e32 v158, v158
	v_exp_f32_e32 v159, v159
	v_exp_f32_e32 v160, v160
	v_exp_f32_e32 v161, v161
	v_pk_add_f32 v[154:155], v[154:155], vcc op_sel_hi:[1,0]
	v_pk_add_f32 v[156:157], v[156:157], vcc op_sel_hi:[1,0]
	v_pk_add_f32 v[158:159], v[158:159], vcc op_sel_hi:[1,0]
	v_pk_add_f32 v[160:161], v[160:161], vcc op_sel_hi:[1,0]
	v_rcp_f32_e32 v154, v154
	v_rcp_f32_e32 v155, v155
	v_rcp_f32_e32 v156, v156
	v_rcp_f32_e32 v157, v157
	v_rcp_f32_e32 v158, v158
	v_rcp_f32_e32 v159, v159
	v_rcp_f32_e32 v160, v160
	v_rcp_f32_e32 v161, v161
	v_pk_mul_f32 v[154:155], v[72:73], v[154:155]
	v_pk_mul_f32 v[156:157], v[74:75], v[156:157]
	v_pk_mul_f32 v[158:159], v[76:77], v[158:159]
	v_pk_mul_f32 v[160:161], v[78:79], v[160:161]
	v_cvt_pk_bf16_f32 v72, v158, v159
	v_cvt_pk_bf16_f32 v73, v160, v161
	v_cvt_pk_bf16_f32 v74, v154, v155
	v_cvt_pk_bf16_f32 v75, v156, v157
	global_store_dwordx4 v162, v[72:75], s[50:51]
	v_pk_mul_f32 v[154:155], v[64:65], s[98:99] op_sel_hi:[1,0]
	v_pk_mul_f32 v[156:157], v[66:67], s[98:99] op_sel_hi:[1,0]
	v_pk_mul_f32 v[158:159], v[68:69], s[98:99] op_sel_hi:[1,0]
	v_pk_mul_f32 v[160:161], v[70:71], s[98:99] op_sel_hi:[1,0]
	v_pk_fma_f32 v[154:155], v[64:65], v[154:155], s[100:101] op_sel_hi:[1,1,0]
	v_pk_fma_f32 v[156:157], v[66:67], v[156:157], s[100:101] op_sel_hi:[1,1,0]
	v_pk_fma_f32 v[158:159], v[68:69], v[158:159], s[100:101] op_sel_hi:[1,1,0]
	v_pk_fma_f32 v[160:161], v[70:71], v[160:161], s[100:101] op_sel_hi:[1,1,0]
	v_pk_mul_f32 v[154:155], v[64:65], v[154:155]
	v_pk_mul_f32 v[156:157], v[66:67], v[156:157]
	v_pk_mul_f32 v[158:159], v[68:69], v[158:159]
	v_pk_mul_f32 v[160:161], v[70:71], v[160:161]
	v_exp_f32_e32 v154, v154
	v_exp_f32_e32 v155, v155
	v_exp_f32_e32 v156, v156
	v_exp_f32_e32 v157, v157
	v_exp_f32_e32 v158, v158
	v_exp_f32_e32 v159, v159
	v_exp_f32_e32 v160, v160
	v_exp_f32_e32 v161, v161
	v_pk_add_f32 v[154:155], v[154:155], vcc op_sel_hi:[1,0]
	v_pk_add_f32 v[156:157], v[156:157], vcc op_sel_hi:[1,0]
	v_pk_add_f32 v[158:159], v[158:159], vcc op_sel_hi:[1,0]
	v_pk_add_f32 v[160:161], v[160:161], vcc op_sel_hi:[1,0]
	v_rcp_f32_e32 v154, v154
	v_rcp_f32_e32 v155, v155
	v_rcp_f32_e32 v156, v156
	v_rcp_f32_e32 v157, v157
	v_rcp_f32_e32 v158, v158
	v_rcp_f32_e32 v159, v159
	v_rcp_f32_e32 v160, v160
	v_rcp_f32_e32 v161, v161
	v_pk_mul_f32 v[154:155], v[64:65], v[154:155]
	v_pk_mul_f32 v[156:157], v[66:67], v[156:157]
	v_pk_mul_f32 v[158:159], v[68:69], v[158:159]
	v_pk_mul_f32 v[160:161], v[70:71], v[160:161]
	v_cvt_pk_bf16_f32 v64, v158, v159
	v_cvt_pk_bf16_f32 v65, v160, v161
	v_cvt_pk_bf16_f32 v66, v154, v155
	v_cvt_pk_bf16_f32 v67, v156, v157
	global_store_dwordx4 v153, v[64:67], s[50:51]
	s_addk_i32 s52, 0x80
	v_or_b32_e32 v153, s52, v146
	v_lshlrev_b32_e32 v153, 4, v153
	v_and_b32_e32 v153, 0x7cf0, v153
	s_ashr_i32 s21, s52, 7
	s_and_b32 s50, s21, -16
	s_ashr_i32 s51, s50, 31
	s_lshl_b64 s[50:51], s[50:51], 1
	s_add_u32 s50, s50, s36
	s_addc_u32 s51, s51, s37
	v_add_u32_e32 v162, v153, v148
	v_add_u32_e32 v153, v153, v149
	v_lshl_add_u32 v162, v162, 10, v136
	v_lshl_add_u32 v153, v153, 10, v136
	v_pk_mul_f32 v[154:155], v[56:57], s[98:99] op_sel_hi:[1,0]
	v_pk_mul_f32 v[156:157], v[58:59], s[98:99] op_sel_hi:[1,0]
	v_pk_mul_f32 v[158:159], v[60:61], s[98:99] op_sel_hi:[1,0]
	v_pk_mul_f32 v[160:161], v[62:63], s[98:99] op_sel_hi:[1,0]
	v_pk_fma_f32 v[154:155], v[56:57], v[154:155], s[100:101] op_sel_hi:[1,1,0]
	v_pk_fma_f32 v[156:157], v[58:59], v[156:157], s[100:101] op_sel_hi:[1,1,0]
	v_pk_fma_f32 v[158:159], v[60:61], v[158:159], s[100:101] op_sel_hi:[1,1,0]
	v_pk_fma_f32 v[160:161], v[62:63], v[160:161], s[100:101] op_sel_hi:[1,1,0]
	v_pk_mul_f32 v[154:155], v[56:57], v[154:155]
	v_pk_mul_f32 v[156:157], v[58:59], v[156:157]
	v_pk_mul_f32 v[158:159], v[60:61], v[158:159]
	v_pk_mul_f32 v[160:161], v[62:63], v[160:161]
	v_exp_f32_e32 v154, v154
	v_exp_f32_e32 v155, v155
	v_exp_f32_e32 v156, v156
	v_exp_f32_e32 v157, v157
	v_exp_f32_e32 v158, v158
	v_exp_f32_e32 v159, v159
	v_exp_f32_e32 v160, v160
	v_exp_f32_e32 v161, v161
	v_pk_add_f32 v[154:155], v[154:155], vcc op_sel_hi:[1,0]
	v_pk_add_f32 v[156:157], v[156:157], vcc op_sel_hi:[1,0]
	v_pk_add_f32 v[158:159], v[158:159], vcc op_sel_hi:[1,0]
	v_pk_add_f32 v[160:161], v[160:161], vcc op_sel_hi:[1,0]
	v_rcp_f32_e32 v154, v154
	v_rcp_f32_e32 v155, v155
	v_rcp_f32_e32 v156, v156
	v_rcp_f32_e32 v157, v157
	v_rcp_f32_e32 v158, v158
	v_rcp_f32_e32 v159, v159
	v_rcp_f32_e32 v160, v160
	v_rcp_f32_e32 v161, v161
	v_pk_mul_f32 v[154:155], v[56:57], v[154:155]
	v_pk_mul_f32 v[156:157], v[58:59], v[156:157]
	v_pk_mul_f32 v[158:159], v[60:61], v[158:159]
	v_pk_mul_f32 v[160:161], v[62:63], v[160:161]
	v_cvt_pk_bf16_f32 v56, v158, v159
; #define GAS __attribute__((address_space(1)))
; __device__ __forceinline__ float fexp2(float x) { return __builtin_amdgcn_exp2f(x); }
; __device__ __forceinline__ float frcp(float x) { return __builtin_amdgcn_rcpf(x); }
; __device__ __forceinline__ float gelu_tanh(float x) { const float u = 0.7978845608028654f * (x + 0.044715f * x * x * x); return x * sigmoidf_(2.f * u); }
; __device__ __forceinline__ u32x4 pack8(f32x4 a, f32x4 b) { u32x4 w; w.x = pk2(a[0], a[1]); w.y = pk2(a[2], a[3]); w.z = pk2(b[0], b[1]); w.w = pk2(b[2], b[3]); return w; }
; __device__ __forceinline__ float sigmoidf_(float x) { return frcp(1.f + fexp2(-x * LOG2E)); }
; __device__ __forceinline__ float siluf_(float x) { return x * sigmoidf_(x); }
;     __device__ __forceinline__ void operator()(const Unit& u, int row, int col, f32x4 v0, f32x4 v1) const {
;         const int g = row >> 11, rowg = row & 2047, j = col >> 4, p = col & 15;
; #pragma unroll
;         for (int i = 0; i < 4; ++i) { v0[i] = gelu_tanh(v0[i]); v1[i] = gelu_tanh(v1[i]); }
;         *(GAS u32x4*)(Y + ((size_t)(rowg * 16 + j) * 512 + g * 16 + p)) = pack8(v0, v1);
	v_cvt_pk_bf16_f32 v57, v160, v161
	v_cvt_pk_bf16_f32 v58, v154, v155
	v_cvt_pk_bf16_f32 v59, v156, v157
	global_store_dwordx4 v162, v[56:59], s[50:51]
	v_pk_mul_f32 v[154:155], v[48:49], s[98:99] op_sel_hi:[1,0]
	v_pk_mul_f32 v[156:157], v[50:51], s[98:99] op_sel_hi:[1,0]
	v_pk_mul_f32 v[158:159], v[52:53], s[98:99] op_sel_hi:[1,0]
	v_pk_mul_f32 v[160:161], v[54:55], s[98:99] op_sel_hi:[1,0]
	v_pk_fma_f32 v[154:155], v[48:49], v[154:155], s[100:101] op_sel_hi:[1,1,0]
	v_pk_fma_f32 v[156:157], v[50:51], v[156:157], s[100:101] op_sel_hi:[1,1,0]
	v_pk_fma_f32 v[158:159], v[52:53], v[158:159], s[100:101] op_sel_hi:[1,1,0]
	v_pk_fma_f32 v[160:161], v[54:55], v[160:161], s[100:101] op_sel_hi:[1,1,0]
	v_pk_mul_f32 v[154:155], v[48:49], v[154:155]
	v_pk_mul_f32 v[156:157], v[50:51], v[156:157]
	v_pk_mul_f32 v[158:159], v[52:53], v[158:159]
	v_pk_mul_f32 v[160:161], v[54:55], v[160:161]
	v_exp_f32_e32 v154, v154
	v_exp_f32_e32 v155, v155
	v_exp_f32_e32 v156, v156
	v_exp_f32_e32 v157, v157
	v_exp_f32_e32 v158, v158
	v_exp_f32_e32 v159, v159
	v_exp_f32_e32 v160, v160
	v_exp_f32_e32 v161, v161
	v_pk_add_f32 v[154:155], v[154:155], vcc op_sel_hi:[1,0]
	v_pk_add_f32 v[156:157], v[156:157], vcc op_sel_hi:[1,0]
	v_pk_add_f32 v[158:159], v[158:159], vcc op_sel_hi:[1,0]
	v_pk_add_f32 v[160:161], v[160:161], vcc op_sel_hi:[1,0]
	v_rcp_f32_e32 v154, v154
	v_rcp_f32_e32 v155, v155
	v_rcp_f32_e32 v156, v156
	v_rcp_f32_e32 v157, v157
	v_rcp_f32_e32 v158, v158
	v_rcp_f32_e32 v159, v159
	v_rcp_f32_e32 v160, v160
	v_rcp_f32_e32 v161, v161
	v_pk_mul_f32 v[154:155], v[48:49], v[154:155]
	v_pk_mul_f32 v[156:157], v[50:51], v[156:157]
	v_pk_mul_f32 v[158:159], v[52:53], v[158:159]
	v_pk_mul_f32 v[160:161], v[54:55], v[160:161]
	v_cvt_pk_bf16_f32 v48, v158, v159
	v_cvt_pk_bf16_f32 v49, v160, v161
	v_cvt_pk_bf16_f32 v50, v154, v155
	v_cvt_pk_bf16_f32 v51, v156, v157
	global_store_dwordx4 v153, v[48:51], s[50:51]
	s_add_u32 s50, s50, 0x40000
	s_addc_u32 s51, s51, 0
	v_pk_mul_f32 v[154:155], v[40:41], s[98:99] op_sel_hi:[1,0]
	v_pk_mul_f32 v[156:157], v[42:43], s[98:99] op_sel_hi:[1,0]
	v_pk_mul_f32 v[158:159], v[44:45], s[98:99] op_sel_hi:[1,0]
	v_pk_mul_f32 v[160:161], v[46:47], s[98:99] op_sel_hi:[1,0]
	v_pk_fma_f32 v[154:155], v[40:41], v[154:155], s[100:101] op_sel_hi:[1,1,0]
	v_pk_fma_f32 v[156:157], v[42:43], v[156:157], s[100:101] op_sel_hi:[1,1,0]
	v_pk_fma_f32 v[158:159], v[44:45], v[158:159], s[100:101] op_sel_hi:[1,1,0]
	v_pk_fma_f32 v[160:161], v[46:47], v[160:161], s[100:101] op_sel_hi:[1,1,0]
	v_pk_mul_f32 v[154:155], v[40:41], v[154:155]
	v_pk_mul_f32 v[156:157], v[42:43], v[156:157]
	v_pk_mul_f32 v[158:159], v[44:45], v[158:159]
	v_pk_mul_f32 v[160:161], v[46:47], v[160:161]
	v_exp_f32_e32 v154, v154
	v_exp_f32_e32 v155, v155
	v_exp_f32_e32 v156, v156
	v_exp_f32_e32 v157, v157
	v_exp_f32_e32 v158, v158
	v_exp_f32_e32 v159, v159
	v_exp_f32_e32 v160, v160
	v_exp_f32_e32 v161, v161
	v_pk_add_f32 v[154:155], v[154:155], vcc op_sel_hi:[1,0]
	v_pk_add_f32 v[156:157], v[156:157], vcc op_sel_hi:[1,0]
	v_pk_add_f32 v[158:159], v[158:159], vcc op_sel_hi:[1,0]
	v_pk_add_f32 v[160:161], v[160:161], vcc op_sel_hi:[1,0]
	v_rcp_f32_e32 v154, v154
	v_rcp_f32_e32 v155, v155
	v_rcp_f32_e32 v156, v156
	v_rcp_f32_e32 v157, v157
	v_rcp_f32_e32 v158, v158
	v_rcp_f32_e32 v159, v159
	v_rcp_f32_e32 v160, v160
	v_rcp_f32_e32 v161, v161
	v_pk_mul_f32 v[154:155], v[40:41], v[154:155]
	v_pk_mul_f32 v[156:157], v[42:43], v[156:157]
	v_pk_mul_f32 v[158:159], v[44:45], v[158:159]
	v_pk_mul_f32 v[160:161], v[46:47], v[160:161]
	v_cvt_pk_bf16_f32 v40, v158, v159
	v_cvt_pk_bf16_f32 v41, v160, v161
	v_cvt_pk_bf16_f32 v42, v154, v155
	v_cvt_pk_bf16_f32 v43, v156, v157
	global_store_dwordx4 v162, v[40:43], s[50:51]
	v_pk_mul_f32 v[154:155], v[32:33], s[98:99] op_sel_hi:[1,0]
	v_pk_mul_f32 v[156:157], v[34:35], s[98:99] op_sel_hi:[1,0]
	v_pk_mul_f32 v[158:159], v[36:37], s[98:99] op_sel_hi:[1,0]
	v_pk_mul_f32 v[160:161], v[38:39], s[98:99] op_sel_hi:[1,0]
	v_pk_fma_f32 v[154:155], v[32:33], v[154:155], s[100:101] op_sel_hi:[1,1,0]
	v_pk_fma_f32 v[156:157], v[34:35], v[156:157], s[100:101] op_sel_hi:[1,1,0]
	v_pk_fma_f32 v[158:159], v[36:37], v[158:159], s[100:101] op_sel_hi:[1,1,0]
	v_pk_fma_f32 v[160:161], v[38:39], v[160:161], s[100:101] op_sel_hi:[1,1,0]
	v_pk_mul_f32 v[154:155], v[32:33], v[154:155]
	v_pk_mul_f32 v[156:157], v[34:35], v[156:157]
	v_pk_mul_f32 v[158:159], v[36:37], v[158:159]
	v_pk_mul_f32 v[160:161], v[38:39], v[160:161]
	v_exp_f32_e32 v154, v154
	v_exp_f32_e32 v155, v155
	v_exp_f32_e32 v156, v156
	v_exp_f32_e32 v157, v157
	v_exp_f32_e32 v158, v158
	v_exp_f32_e32 v159, v159
	v_exp_f32_e32 v160, v160
	v_exp_f32_e32 v161, v161
	v_pk_add_f32 v[154:155], v[154:155], vcc op_sel_hi:[1,0]
	v_pk_add_f32 v[156:157], v[156:157], vcc op_sel_hi:[1,0]
	v_pk_add_f32 v[158:159], v[158:159], vcc op_sel_hi:[1,0]
	v_pk_add_f32 v[160:161], v[160:161], vcc op_sel_hi:[1,0]
	v_rcp_f32_e32 v154, v154
	v_rcp_f32_e32 v155, v155
	v_rcp_f32_e32 v156, v156
	v_rcp_f32_e32 v157, v157
	v_rcp_f32_e32 v158, v158
	v_rcp_f32_e32 v159, v159
	v_rcp_f32_e32 v160, v160
	v_rcp_f32_e32 v161, v161
	v_pk_mul_f32 v[154:155], v[32:33], v[154:155]
	v_pk_mul_f32 v[156:157], v[34:35], v[156:157]
	v_pk_mul_f32 v[158:159], v[36:37], v[158:159]
	v_pk_mul_f32 v[160:161], v[38:39], v[160:161]
	v_cvt_pk_bf16_f32 v32, v158, v159
	v_cvt_pk_bf16_f32 v33, v160, v161
	v_cvt_pk_bf16_f32 v34, v154, v155
	v_cvt_pk_bf16_f32 v35, v156, v157
	global_store_dwordx4 v153, v[32:35], s[50:51]
	s_add_u32 s50, s50, 0x40000
	s_addc_u32 s51, s51, 0
	v_pk_mul_f32 v[154:155], v[24:25], s[98:99] op_sel_hi:[1,0]
	v_pk_mul_f32 v[156:157], v[26:27], s[98:99] op_sel_hi:[1,0]
; #define GAS __attribute__((address_space(1)))
; __device__ __forceinline__ float gelu_tanh(float x) { const float u = 0.7978845608028654f * (x + 0.044715f * x * x * x); return x * sigmoidf_(2.f * u); }
; #define PG8_BAR __builtin_amdgcn_s_barrier()
; __device__ __forceinline__ u32x4 pack8(f32x4 a, f32x4 b) { u32x4 w; w.x = pk2(a[0], a[1]); w.y = pk2(a[2], a[3]); w.z = pk2(b[0], b[1]); w.w = pk2(b[2], b[3]); return w; }
; template <class Epi, class Sched>
; __device__ __forceinline__ void gemm_phase(LAS unsigned char* lds, const Gemm g, const Sched& S, const Epi& E, const int wave_) {
;     ...
;         if (wr == 0) PG8_BAR;
;         E(acc, cur, wr, wc, fr, fq);
;         if (!has_next) break;
;     __device__ __forceinline__ void operator()(const Unit& u, int row, int col, f32x4 v0, f32x4 v1) const {
;         const int g = row >> 11, rowg = row & 2047, j = col >> 4, p = col & 15;
; #pragma unroll
;         for (int i = 0; i < 4; ++i) { v0[i] = gelu_tanh(v0[i]); v1[i] = gelu_tanh(v1[i]); }
;         *(GAS u32x4*)(Y + ((size_t)(rowg * 16 + j) * 512 + g * 16 + p)) = pack8(v0, v1);
	v_pk_mul_f32 v[158:159], v[28:29], s[98:99] op_sel_hi:[1,0]
	v_pk_mul_f32 v[160:161], v[30:31], s[98:99] op_sel_hi:[1,0]
	v_pk_fma_f32 v[154:155], v[24:25], v[154:155], s[100:101] op_sel_hi:[1,1,0]
	v_pk_fma_f32 v[156:157], v[26:27], v[156:157], s[100:101] op_sel_hi:[1,1,0]
	v_pk_fma_f32 v[158:159], v[28:29], v[158:159], s[100:101] op_sel_hi:[1,1,0]
	v_pk_fma_f32 v[160:161], v[30:31], v[160:161], s[100:101] op_sel_hi:[1,1,0]
	v_pk_mul_f32 v[154:155], v[24:25], v[154:155]
	v_pk_mul_f32 v[156:157], v[26:27], v[156:157]
	v_pk_mul_f32 v[158:159], v[28:29], v[158:159]
	v_pk_mul_f32 v[160:161], v[30:31], v[160:161]
	v_exp_f32_e32 v154, v154
	v_exp_f32_e32 v155, v155
	v_exp_f32_e32 v156, v156
	v_exp_f32_e32 v157, v157
	v_exp_f32_e32 v158, v158
	v_exp_f32_e32 v159, v159
	v_exp_f32_e32 v160, v160
	v_exp_f32_e32 v161, v161
	v_pk_add_f32 v[154:155], v[154:155], vcc op_sel_hi:[1,0]
	v_pk_add_f32 v[156:157], v[156:157], vcc op_sel_hi:[1,0]
	v_pk_add_f32 v[158:159], v[158:159], vcc op_sel_hi:[1,0]
	v_pk_add_f32 v[160:161], v[160:161], vcc op_sel_hi:[1,0]
	v_rcp_f32_e32 v154, v154
	v_rcp_f32_e32 v155, v155
	v_rcp_f32_e32 v156, v156
	v_rcp_f32_e32 v157, v157
	v_rcp_f32_e32 v158, v158
	v_rcp_f32_e32 v159, v159
	v_rcp_f32_e32 v160, v160
	v_rcp_f32_e32 v161, v161
	v_pk_mul_f32 v[154:155], v[24:25], v[154:155]
	v_pk_mul_f32 v[156:157], v[26:27], v[156:157]
	v_pk_mul_f32 v[158:159], v[28:29], v[158:159]
	v_pk_mul_f32 v[160:161], v[30:31], v[160:161]
	v_cvt_pk_bf16_f32 v24, v158, v159
	v_cvt_pk_bf16_f32 v25, v160, v161
	v_cvt_pk_bf16_f32 v26, v154, v155
	v_cvt_pk_bf16_f32 v27, v156, v157
	global_store_dwordx4 v162, v[24:27], s[50:51]
	v_pk_mul_f32 v[154:155], v[16:17], s[98:99] op_sel_hi:[1,0]
	v_pk_mul_f32 v[156:157], v[18:19], s[98:99] op_sel_hi:[1,0]
	v_pk_mul_f32 v[158:159], v[20:21], s[98:99] op_sel_hi:[1,0]
	v_pk_mul_f32 v[160:161], v[22:23], s[98:99] op_sel_hi:[1,0]
	v_pk_fma_f32 v[154:155], v[16:17], v[154:155], s[100:101] op_sel_hi:[1,1,0]
	v_pk_fma_f32 v[156:157], v[18:19], v[156:157], s[100:101] op_sel_hi:[1,1,0]
	v_pk_fma_f32 v[158:159], v[20:21], v[158:159], s[100:101] op_sel_hi:[1,1,0]
	v_pk_fma_f32 v[160:161], v[22:23], v[160:161], s[100:101] op_sel_hi:[1,1,0]
	v_pk_mul_f32 v[154:155], v[16:17], v[154:155]
	v_pk_mul_f32 v[156:157], v[18:19], v[156:157]
	v_pk_mul_f32 v[158:159], v[20:21], v[158:159]
	v_pk_mul_f32 v[160:161], v[22:23], v[160:161]
	v_exp_f32_e32 v154, v154
	v_exp_f32_e32 v155, v155
	v_exp_f32_e32 v156, v156
	v_exp_f32_e32 v157, v157
	v_exp_f32_e32 v158, v158
	v_exp_f32_e32 v159, v159
	v_exp_f32_e32 v160, v160
	v_exp_f32_e32 v161, v161
	v_pk_add_f32 v[154:155], v[154:155], vcc op_sel_hi:[1,0]
	v_pk_add_f32 v[156:157], v[156:157], vcc op_sel_hi:[1,0]
	v_pk_add_f32 v[158:159], v[158:159], vcc op_sel_hi:[1,0]
	v_pk_add_f32 v[160:161], v[160:161], vcc op_sel_hi:[1,0]
	v_rcp_f32_e32 v154, v154
	v_rcp_f32_e32 v155, v155
	v_rcp_f32_e32 v156, v156
	v_rcp_f32_e32 v157, v157
	v_rcp_f32_e32 v158, v158
	v_rcp_f32_e32 v159, v159
	v_rcp_f32_e32 v160, v160
	v_rcp_f32_e32 v161, v161
	v_pk_mul_f32 v[154:155], v[16:17], v[154:155]
	v_pk_mul_f32 v[156:157], v[18:19], v[156:157]
	v_pk_mul_f32 v[158:159], v[20:21], v[158:159]
	v_pk_mul_f32 v[160:161], v[22:23], v[160:161]
	v_cvt_pk_bf16_f32 v16, v158, v159
	v_cvt_pk_bf16_f32 v17, v160, v161
	v_cvt_pk_bf16_f32 v18, v154, v155
	v_cvt_pk_bf16_f32 v19, v156, v157
	global_store_dwordx4 v153, v[16:19], s[50:51]
	s_add_u32 s50, s50, 0x40000
	s_addc_u32 s51, s51, 0
	v_pk_mul_f32 v[154:155], v[8:9], s[98:99] op_sel_hi:[1,0]
	v_pk_mul_f32 v[156:157], v[10:11], s[98:99] op_sel_hi:[1,0]
	v_pk_mul_f32 v[158:159], v[12:13], s[98:99] op_sel_hi:[1,0]
	v_pk_mul_f32 v[160:161], v[14:15], s[98:99] op_sel_hi:[1,0]
	v_pk_fma_f32 v[154:155], v[8:9], v[154:155], s[100:101] op_sel_hi:[1,1,0]
	v_pk_fma_f32 v[156:157], v[10:11], v[156:157], s[100:101] op_sel_hi:[1,1,0]
	v_pk_fma_f32 v[158:159], v[12:13], v[158:159], s[100:101] op_sel_hi:[1,1,0]
	v_pk_fma_f32 v[160:161], v[14:15], v[160:161], s[100:101] op_sel_hi:[1,1,0]
	v_pk_mul_f32 v[154:155], v[8:9], v[154:155]
	v_pk_mul_f32 v[156:157], v[10:11], v[156:157]
	v_pk_mul_f32 v[158:159], v[12:13], v[158:159]
	v_pk_mul_f32 v[160:161], v[14:15], v[160:161]
	v_exp_f32_e32 v154, v154
	v_exp_f32_e32 v155, v155
	v_exp_f32_e32 v156, v156
	v_exp_f32_e32 v157, v157
	v_exp_f32_e32 v158, v158
	v_exp_f32_e32 v159, v159
	v_exp_f32_e32 v160, v160
	v_exp_f32_e32 v161, v161
	v_pk_add_f32 v[154:155], v[154:155], vcc op_sel_hi:[1,0]
	v_pk_add_f32 v[156:157], v[156:157], vcc op_sel_hi:[1,0]
	v_pk_add_f32 v[158:159], v[158:159], vcc op_sel_hi:[1,0]
	v_pk_add_f32 v[160:161], v[160:161], vcc op_sel_hi:[1,0]
	v_rcp_f32_e32 v154, v154
	v_rcp_f32_e32 v155, v155
	v_rcp_f32_e32 v156, v156
	v_rcp_f32_e32 v157, v157
	v_rcp_f32_e32 v158, v158
	v_rcp_f32_e32 v159, v159
	v_rcp_f32_e32 v160, v160
	v_rcp_f32_e32 v161, v161
	v_pk_mul_f32 v[154:155], v[8:9], v[154:155]
	v_pk_mul_f32 v[156:157], v[10:11], v[156:157]
	v_pk_mul_f32 v[158:159], v[12:13], v[158:159]
	v_pk_mul_f32 v[160:161], v[14:15], v[160:161]
	v_cvt_pk_bf16_f32 v8, v158, v159
	v_cvt_pk_bf16_f32 v9, v160, v161
	v_cvt_pk_bf16_f32 v10, v154, v155
	v_cvt_pk_bf16_f32 v11, v156, v157
	global_store_dwordx4 v162, v[8:11], s[50:51]
	v_pk_mul_f32 v[154:155], v[0:1], s[98:99] op_sel_hi:[1,0]
	v_pk_mul_f32 v[156:157], v[2:3], s[98:99] op_sel_hi:[1,0]
	v_pk_mul_f32 v[158:159], v[4:5], s[98:99] op_sel_hi:[1,0]
	v_pk_mul_f32 v[160:161], v[6:7], s[98:99] op_sel_hi:[1,0]
	v_pk_fma_f32 v[154:155], v[0:1], v[154:155], s[100:101] op_sel_hi:[1,1,0]
	v_pk_fma_f32 v[156:157], v[2:3], v[156:157], s[100:101] op_sel_hi:[1,1,0]
	v_pk_fma_f32 v[158:159], v[4:5], v[158:159], s[100:101] op_sel_hi:[1,1,0]
	v_pk_fma_f32 v[160:161], v[6:7], v[160:161], s[100:101] op_sel_hi:[1,1,0]
	v_pk_mul_f32 v[154:155], v[0:1], v[154:155]
	v_pk_mul_f32 v[156:157], v[2:3], v[156:157]
	v_pk_mul_f32 v[158:159], v[4:5], v[158:159]
	v_pk_mul_f32 v[160:161], v[6:7], v[160:161]
	v_exp_f32_e32 v154, v154
	v_exp_f32_e32 v155, v155
	v_exp_f32_e32 v156, v156
	v_exp_f32_e32 v157, v157
	v_exp_f32_e32 v158, v158
	v_exp_f32_e32 v159, v159
	v_exp_f32_e32 v160, v160
	v_exp_f32_e32 v161, v161
	v_pk_add_f32 v[154:155], v[154:155], vcc op_sel_hi:[1,0]
	v_pk_add_f32 v[156:157], v[156:157], vcc op_sel_hi:[1,0]
	v_pk_add_f32 v[158:159], v[158:159], vcc op_sel_hi:[1,0]
	v_pk_add_f32 v[160:161], v[160:161], vcc op_sel_hi:[1,0]
	v_rcp_f32_e32 v154, v154
	v_rcp_f32_e32 v155, v155
	v_rcp_f32_e32 v156, v156
	v_rcp_f32_e32 v157, v157
	v_rcp_f32_e32 v158, v158
	v_rcp_f32_e32 v159, v159
	v_rcp_f32_e32 v160, v160
	v_rcp_f32_e32 v161, v161
	v_pk_mul_f32 v[154:155], v[0:1], v[154:155]
	v_pk_mul_f32 v[156:157], v[2:3], v[156:157]
	v_pk_mul_f32 v[158:159], v[4:5], v[158:159]
	v_pk_mul_f32 v[160:161], v[6:7], v[160:161]
	v_cvt_pk_bf16_f32 v0, v158, v159
	v_cvt_pk_bf16_f32 v1, v160, v161
	v_cvt_pk_bf16_f32 v2, v154, v155
	v_cvt_pk_bf16_f32 v3, v156, v157
	global_store_dwordx4 v153, v[0:3], s[50:51]
	s_andn2_b64 vcc, exec, s[8:9]
	s_mov_b64 s[8:9], -1
	s_cbranch_vccnz .LBB0_691
; #define PG8_BAR __builtin_amdgcn_s_barrier()
; template <class Epi, class Sched>
; __device__ __forceinline__ void gemm_phase(LAS unsigned char* lds, const Gemm g, const Sched& S, const Epi& E, const int wave_) {
;     ...
;         cur = nxt; cA = nA; cB = nB; ++ui;
;         if (wr == 1) PG8_BAR;
;     }
	s_andn2_b64 vcc, exec, s[34:35]
	s_cbranch_vccnz .LBB0_690
	s_barrier
	s_branch .LBB0_690
